# prompt SSD chunk loop: LDS fragment reads of the state-update and y blocks issued as batches with counted waits
# speedup vs baseline: 1.0578x; 1.0004x over previous
; #define LAS __attribute__((address_space(3)))
; __device__ __forceinline__ unsigned pk2(float lo, float hi) { unsigned r; asm("v_cvt_pk_bf16_f32 %0, %1, %2" : "=v"(r) : "v"(lo), "v"(hi)); return r; }
; #define LDS_BARRIER() do { asm volatile("s_waitcnt lgkmcnt(0)" ::: "memory"); __builtin_amdgcn_s_barrier(); asm volatile("" ::: "memory"); } while (0)
; #define MFMA16(a, b, c) __builtin_amdgcn_mfma_f32_16x16x32_bf16((a), (b), (c), 0, 0, 0)
; __device__ __forceinline__ void ssd_prompt(LAS unsigned char* lds, int b, int h, const bf16_t* XBC, const float* CS, const bf16_t* XT1, const bf16_t* XT2, const bf16_t* BT, bf16_t* MIX, float* p_ssm) {
;     ...
;         for (int pt = 0; pt < 4; ++pt) { u32x2 pk; pk.x = pk2(yacc[pt][0], yacc[pt][1]); pk.y = pk2(yacc[pt][2], yacc[pt][3]);
;             *(u32x2*)(MIX + (size_t)(rowbase + 16 * rt + fr) * DMIX + h * 64 + 16 * pt + 4 * fq) = pk; }
;         { const float dl = __expf(cs_last);
; #pragma unroll
;           for (int pt = 0; pt < 4; ++pt) hacc[pt] *= dl; }
; #pragma unroll
;         for (int ks = 0; ks < 4; ++ks) { const bf16x8 bb = *(const LAS bf16x8*)(BTs + (16 * w + fr) * LDP + ks * 32 + fq * 8);
; #pragma unroll
;             for (int pt = 0; pt < 4; ++pt) { const bf16x8 aa = *(const LAS bf16x8*)(X2s + (16 * pt + fr) * LDP + ks * 32 + fq * 8); hacc[pt] = MFMA16(bb, aa, hacc[pt]); } }
;         LDS_BARRIER();
; #pragma unroll
;         for (int pt = 0; pt < 4; ++pt) { u32x2 pk; pk.x = pk2(hacc[pt][0], hacc[pt][1]); pk.y = pk2(hacc[pt][2], hacc[pt][3]);
;             *(LAS u32x2*)(Hs + (16 * pt + fr) * LDP + 16 * w + 4 * fq) = pk; }
.LBB0_448:
	v_ashrrev_i32_e32 v133, 31, v132
	v_lshlrev_b64 v[132:133], 13, v[132:133]
	v_lshl_add_u64 v[132:133], v[106:107], 0, v[132:133]
	v_cvt_pk_bf16_f32 v80, v80, v81
	v_cvt_pk_bf16_f32 v81, v82, v83
	global_store_dwordx2 v[132:133], v[80:81], off
	v_cvt_pk_bf16_f32 v80, v84, v85
	v_cvt_pk_bf16_f32 v81, v86, v87
	global_store_dwordx2 v[132:133], v[80:81], off offset:32
	v_cvt_pk_bf16_f32 v80, v88, v89
	v_cvt_pk_bf16_f32 v81, v90, v91
	global_store_dwordx2 v[132:133], v[80:81], off offset:64
	v_cvt_pk_bf16_f32 v80, v92, v93
	v_cvt_pk_bf16_f32 v81, v94, v95
	global_store_dwordx2 v[132:133], v[80:81], off offset:96
	v_mul_f32_e32 v80, 0x3fb8aa3b, v163
	v_exp_f32_e32 v80, v80
	s_addk_i32 s17, 0x200
	s_addk_i32 s16, 0x80
	s_waitcnt vmcnt(7)
	v_mov_b64_e32 v[90:91], v[54:55]
	v_pk_mul_f32 v[66:67], v[66:67], v[80:81] op_sel_hi:[1,0]
	v_pk_mul_f32 v[64:65], v[64:65], v[80:81] op_sel_hi:[1,0]
	v_pk_mul_f32 v[70:71], v[70:71], v[80:81] op_sel_hi:[1,0]
	v_pk_mul_f32 v[68:69], v[68:69], v[80:81] op_sel_hi:[1,0]
	v_pk_mul_f32 v[74:75], v[74:75], v[80:81] op_sel_hi:[1,0]
	v_pk_mul_f32 v[72:73], v[72:73], v[80:81] op_sel_hi:[1,0]
	v_pk_mul_f32 v[78:79], v[78:79], v[80:81] op_sel_hi:[1,0]
	v_pk_mul_f32 v[76:77], v[76:77], v[80:81] op_sel_hi:[1,0]
	ds_read_b128 v[80:83], v108 offset:34816
	ds_read_b128 v[176:179], v160
	ds_read_b128 v[180:183], v160 offset:4352
	ds_read_b128 v[184:187], v160 offset:8704
	ds_read_b128 v[188:191], v160 offset:13056
	ds_read_b128 v[84:87], v108 offset:34880
	ds_read_b128 v[192:195], v160 offset:64
	ds_read_b128 v[196:199], v160 offset:4416
	ds_read_b128 v[200:203], v160 offset:8768
	ds_read_b128 v[204:207], v160 offset:13120
	ds_read_b128 v[244:247], v108 offset:34944
	ds_read_b128 v[208:211], v160 offset:128
	ds_read_b128 v[216:219], v160 offset:4480
	ds_read_b128 v[220:223], v160 offset:8832
	ds_read_b128 v[224:227], v160 offset:13184
	ds_read_b128 v[248:251], v108 offset:35008
	ds_read_b128 v[228:231], v160 offset:192
	ds_read_b128 v[232:235], v160 offset:4544
	ds_read_b128 v[236:239], v160 offset:8896
	ds_read_b128 v[240:243], v160 offset:13248
	s_waitcnt vmcnt(5)
	v_mov_b64_e32 v[94:95], v[62:63]
	v_lshl_add_u64 v[124:125], v[124:125], 0, s[92:93]
	v_lshl_add_u64 v[126:127], v[126:127], 0, s[92:93]
	v_lshl_add_u64 v[128:129], v[128:129], 0, s[92:93]
	v_lshl_add_u64 v[130:131], v[130:131], 0, s[92:93]
	v_lshl_add_u64 v[114:115], v[114:115], 0, s[72:73]
	v_lshl_add_u64 v[116:117], v[116:117], 0, s[72:73]
	v_lshl_add_u64 v[118:119], v[118:119], 0, s[72:73]
	v_lshl_add_u64 v[120:121], v[120:121], 0, s[72:73]
	s_cmpk_lg_i32 s17, 0x2000
	v_mov_b64_e32 v[88:89], v[52:53]
	v_mov_b64_e32 v[92:93], v[60:61]
	s_waitcnt lgkmcnt(15)
	v_mfma_f32_16x16x32_bf16 v[64:67], v[80:83], v[176:179], v[64:67]
	v_mfma_f32_16x16x32_bf16 v[68:71], v[80:83], v[180:183], v[68:71]
	v_mfma_f32_16x16x32_bf16 v[72:75], v[80:83], v[184:187], v[72:75]
	v_mfma_f32_16x16x32_bf16 v[76:79], v[80:83], v[188:191], v[76:79]
	s_waitcnt lgkmcnt(10)
	v_mfma_f32_16x16x32_bf16 v[64:67], v[84:87], v[192:195], v[64:67]
	v_mfma_f32_16x16x32_bf16 v[68:71], v[84:87], v[196:199], v[68:71]
	v_mfma_f32_16x16x32_bf16 v[72:75], v[84:87], v[200:203], v[72:75]
	v_mfma_f32_16x16x32_bf16 v[76:79], v[84:87], v[204:207], v[76:79]
	s_waitcnt lgkmcnt(5)
	v_mfma_f32_16x16x32_bf16 v[64:67], v[244:247], v[208:211], v[64:67]
	v_mfma_f32_16x16x32_bf16 v[68:71], v[244:247], v[216:219], v[68:71]
	v_mfma_f32_16x16x32_bf16 v[72:75], v[244:247], v[220:223], v[72:75]
	v_mfma_f32_16x16x32_bf16 v[76:79], v[244:247], v[224:227], v[76:79]
	s_waitcnt lgkmcnt(0)
	s_barrier
	v_mfma_f32_16x16x32_bf16 v[64:67], v[248:251], v[228:231], v[64:67]
	v_mfma_f32_16x16x32_bf16 v[68:71], v[248:251], v[232:235], v[68:71]
	v_mfma_f32_16x16x32_bf16 v[72:75], v[248:251], v[236:239], v[72:75]
	v_mfma_f32_16x16x32_bf16 v[76:79], v[248:251], v[240:243], v[76:79]
	s_nop 7
	s_nop 1
	v_cvt_pk_bf16_f32 v80, v64, v65
	v_cvt_pk_bf16_f32 v81, v66, v67
	ds_write_b64 v161, v[80:81]
	v_cvt_pk_bf16_f32 v80, v68, v69
	v_cvt_pk_bf16_f32 v81, v70, v71
	ds_write_b64 v161, v[80:81] offset:4352
	v_cvt_pk_bf16_f32 v80, v72, v73
	v_cvt_pk_bf16_f32 v81, v74, v75
	ds_write_b64 v161, v[80:81] offset:8704
	v_cvt_pk_bf16_f32 v80, v76, v77
	v_cvt_pk_bf16_f32 v81, v78, v79
	ds_write_b64 v161, v[80:81] offset:13056
	s_waitcnt vmcnt(4)
	v_mov_b64_e32 v[82:83], v[58:59]
	v_mov_b64_e32 v[86:87], v[50:51]
	v_mov_b64_e32 v[80:81], v[56:57]
	v_mov_b64_e32 v[84:85], v[48:49]
	s_cbranch_scc0 .LBB0_443

; #define LAS __attribute__((address_space(3)))
; #define MFMA16(a, b, c) __builtin_amdgcn_mfma_f32_16x16x32_bf16((a), (b), (c), 0, 0, 0)
; __device__ __forceinline__ void ssd_prompt(LAS unsigned char* lds, int b, int h, const bf16_t* XBC, const float* CS, const bf16_t* XT1, const bf16_t* XT2, const bf16_t* BT, bf16_t* MIX, float* p_ssm) {
;     ...
; #pragma unroll
;         for (int ks = 0; ks < 4; ++ks)
; #pragma unroll
;             for (int pt = 0; pt < 4; ++pt) { const bf16x8 bb = *(const LAS bf16x8*)(Hs + (16 * pt + fr) * LDP + ks * 32 + fq * 8); yacc[pt] = MFMA16(bb, afr[ks], yacc[pt]); }
;         { const float e = __expf(csi);
; #pragma unroll
;           for (int pt = 0; pt < 4; ++pt) yacc[pt] *= e; }
.LBB0_475:
	s_waitcnt lgkmcnt(0)
	ds_read_b128 v[176:179], v159
	ds_read_b128 v[180:183], v159 offset:4352
	ds_read_b128 v[184:187], v159 offset:8704
	ds_read_b128 v[188:191], v159 offset:13056
	ds_read_b128 v[192:195], v159 offset:64
	ds_read_b128 v[196:199], v159 offset:4416
	ds_read_b128 v[200:203], v159 offset:8768
	ds_read_b128 v[204:207], v159 offset:13120
	ds_read_b128 v[208:211], v159 offset:128
	ds_read_b128 v[216:219], v159 offset:4480
	ds_read_b128 v[220:223], v159 offset:8832
	ds_read_b128 v[224:227], v159 offset:13184
	ds_read_b128 v[228:231], v159 offset:192
	ds_read_b128 v[232:235], v159 offset:4544
	ds_read_b128 v[236:239], v159 offset:8896
	ds_read_b128 v[240:243], v159 offset:13248
	s_andn2_b64 vcc, exec, s[8:9]
	s_waitcnt lgkmcnt(12)
	v_mfma_f32_16x16x32_bf16 v[134:137], v[176:179], v[92:95], 0
	v_mfma_f32_16x16x32_bf16 v[138:141], v[180:183], v[92:95], 0
	v_mfma_f32_16x16x32_bf16 v[142:145], v[184:187], v[92:95], 0
	v_mfma_f32_16x16x32_bf16 v[146:149], v[188:191], v[92:95], 0
	s_waitcnt lgkmcnt(8)
	v_mfma_f32_16x16x32_bf16 v[134:137], v[192:195], v[88:91], v[134:137]
	v_mfma_f32_16x16x32_bf16 v[138:141], v[196:199], v[88:91], v[138:141]
	v_mfma_f32_16x16x32_bf16 v[142:145], v[200:203], v[88:91], v[142:145]
	v_mfma_f32_16x16x32_bf16 v[146:149], v[204:207], v[88:91], v[146:149]
	s_waitcnt lgkmcnt(4)
	v_mfma_f32_16x16x32_bf16 v[134:137], v[208:211], v[84:87], v[134:137]
	v_mfma_f32_16x16x32_bf16 v[138:141], v[216:219], v[84:87], v[138:141]
	v_mfma_f32_16x16x32_bf16 v[142:145], v[220:223], v[84:87], v[142:145]
	v_mfma_f32_16x16x32_bf16 v[146:149], v[224:227], v[84:87], v[146:149]
	s_waitcnt lgkmcnt(0)
	v_mfma_f32_16x16x32_bf16 v[134:137], v[228:231], v[80:83], v[134:137]
	v_mfma_f32_16x16x32_bf16 v[138:141], v[232:235], v[80:83], v[138:141]
	v_mfma_f32_16x16x32_bf16 v[142:145], v[236:239], v[80:83], v[142:145]
	v_mfma_f32_16x16x32_bf16 v[146:149], v[240:243], v[80:83], v[146:149]
	s_nop 7
	v_mul_f32_e32 v80, 0x3fb8aa3b, v133
	v_exp_f32_e32 v244, v80
	v_add_u32_e32 v133, v150, v100
	v_pk_mul_f32 v[82:83], v[244:245], v[136:137] op_sel_hi:[0,1]
	v_pk_mul_f32 v[80:81], v[244:245], v[134:135] op_sel_hi:[0,1]
	v_pk_mul_f32 v[86:87], v[244:245], v[140:141] op_sel_hi:[0,1]
	v_pk_mul_f32 v[84:85], v[244:245], v[138:139] op_sel_hi:[0,1]
	v_pk_mul_f32 v[90:91], v[244:245], v[144:145] op_sel_hi:[0,1]
	v_pk_mul_f32 v[88:89], v[244:245], v[142:143] op_sel_hi:[0,1]
	v_pk_mul_f32 v[94:95], v[244:245], v[148:149] op_sel_hi:[0,1]
	v_pk_mul_f32 v[92:93], v[244:245], v[146:147] op_sel_hi:[0,1]
	s_cbranch_vccz .LBB0_485
	s_andn2_b64 vcc, exec, s[10:11]
	s_cbranch_vccz .LBB0_486
